# pair8c plus P0 x-packer block remap: a CU converts rows q, q+1, q+64, q+65 per step so that both writers of every XB8 line sit in one CU
# baseline (speedup 1.0000x reference)
; #define XLOAD(blk_) do { const size_t e0_ = (blk_) * 2048; const float* s0_ = (e0_ < (size_t)SEQ * DM) ? F.xp + e0_ : F.xs + (e0_ - (size_t)SEQ * DM); \
;     _Pragma("unroll") for (int i = 0; i < 4; ++i) { const float* s_ = s0_ + (i * 64 + plane) * 8; la[i] = *(const f32x4*)s_; lb[i] = *(const f32x4*)(s_ + 4); } } while (0)
;     __device__ __forceinline__ unsigned a(const pg8::Unit& u) const { return (unsigned)u.pm * (256u * K * 2u); }
;     __device__ __forceinline__ unsigned a(const pg8::Unit& u) const { return (unsigned)u.pm * (256u * K * 2u); }
;     __device__ __forceinline__ unsigned a(const pg8::Unit& u) const { return (unsigned)u.pm * (256u * K * 2u); }
;     __device__ __forceinline__ unsigned a(const pg8::Unit& u) const { return (unsigned)u.pm * (256u * K * 2u); }
;     __device__ __forceinline__ unsigned a(const pg8::Unit& u) const { return (unsigned)u.pm * (256u * K * 2u); }
; __device__ __forceinline__ void p0_prologue(const Frame& F) {
;     ...
;     {
;         constexpr size_t NB = (size_t)M * DM / 2048;
;         f32x4 la[4], lb[4];
;     ...
;         size_t blk = gw;
;         if (blk < NB) XLOAD(blk);
;         for (; blk < NB; blk += NGW) {
;             const size_t e0 = blk * 2048;
;             f32x4 a[4], b[4];
; #pragma unroll
;             for (int i = 0; i < 4; ++i) { a[i] = la[i]; b[i] = lb[i]; }
;             if (blk + NGW < NB) XLOAD(blk + NGW);
.LBB0_49:
	s_lshr_b32 s0, s50, 1
	s_and_b32 s0, s0, 0x7c
	s_lshl_b32 s1, s50, 5
	s_and_b32 s1, s1, 0x80
	s_andn2_b32 s50, s50, 0xfc
	s_or_b32 s50, s50, s0
	s_or_b32 s50, s50, s1
	s_cmpk_lt_u32 s50, 0xc000
	s_cbranch_scc0 .LBB0_54
	s_mov_b32 s51, 0
	s_lshl_b64 s[4:5], s[50:51], 11
	s_lshl_b64 s[0:1], s[50:51], 13
	s_add_u32 s6, s12, s0
	s_addc_u32 s7, s13, s1
	s_add_u32 s0, s14, s0
	s_addc_u32 s1, s15, s1
	s_add_u32 s0, s0, 0xf8000000
	s_addc_u32 s1, s1, -1
	s_cmpk_lt_u32 s50, 0x4000
	v_mov_b32_e32 v32, 0
	s_cselect_b32 s1, s7, s1
	s_cselect_b32 s0, s6, s0
	v_lshlrev_b32_e32 v36, 5, v35
	v_mov_b32_e32 v37, v32
	v_lshl_add_u64 v[0:1], s[0:1], 0, v[36:37]
	s_movk_i32 s10, 0x1000
	s_mov_b64 s[6:7], 0x1800
	v_add_co_u32_e32 v4, vcc, s10, v0
	s_mov_b64 s[8:9], 0x1000
	v_lshl_add_u64 v[2:3], v[0:1], 0, s[6:7]
	v_addc_co_u32_e32 v5, vcc, 0, v1, vcc
	v_lshl_add_u64 v[0:1], v[0:1], 0, s[8:9]
	global_load_dwordx4 v[24:27], v36, s[0:1] offset:16
	global_load_dwordx4 v[16:19], v36, s[0:1] offset:2064
	global_load_dwordx4 v[8:11], v[0:1], off offset:16
	s_nop 0
	global_load_dwordx4 v[0:3], v[2:3], off offset:16
	s_nop 0
	global_load_dwordx4 v[28:31], v36, s[0:1]
	global_load_dwordx4 v[20:23], v36, s[0:1] offset:2048
	global_load_dwordx4 v[12:15], v[4:5], off
	s_nop 0
	global_load_dwordx4 v[4:7], v[4:5], off offset:2048
	s_ashr_i32 s55, s54, 31
	s_add_u32 s11, s14, 0xf8000000
	s_addc_u32 s33, s15, -1
	s_add_u32 s0, s54, s50
	s_addc_u32 s1, s55, 0
	v_mul_u32_u24_e32 v38, 0x90, v35
	v_lshrrev_b32_e32 v39, 2, v35
	v_or_b32_e32 v40, 64, v35
	v_or_b32_e32 v41, 0x80, v35
	v_or_b32_e32 v35, 0xc0, v35
	s_lshl_b64 s[16:17], s[0:1], 13
	s_lshl_b64 s[58:59], s[54:55], 13
	s_lshl_b64 s[62:63], s[54:55], 11
	s_lshl_b64 s[0:1], s[50:51], 12
	v_lshlrev_b32_e32 v33, 5, v66
	v_and_b32_e32 v34, 0x780, v36
	v_lshrrev_b32_e32 v36, 1, v36
	v_lshrrev_b32_e32 v35, 2, v35
	s_add_u32 s0, s38, s0
	v_and_b32_e32 v33, 0x60, v33
	v_lshrrev_b32_e32 v40, 2, v40
	v_lshrrev_b32_e32 v41, 2, v41
	v_mul_u32_u24_e32 v42, 0x90, v35
	v_and_or_b32 v34, v36, 48, v34
	v_mov_b32_e32 v35, v32
	s_addc_u32 s1, s39, s1
	v_add_u32_e32 v33, s3, v33
	v_mul_u32_u24_e32 v39, 0x90, v39
	v_mul_u32_u24_e32 v40, 0x90, v40
	v_mul_u32_u24_e32 v41, 0x90, v41
	v_lshl_add_u64 v[70:71], s[40:41], 0, v[34:35]
	v_lshl_add_u64 v[34:35], s[0:1], 0, v[36:37]
	s_mov_b64 s[0:1], 0x800
	v_mov_b32_e32 v69, v32
	v_lshl_add_u64 v[72:73], v[34:35], 0, s[0:1]
	v_add_u32_e32 v67, v33, v39
	v_add_u32_e32 v80, v33, v40
	v_add_u32_e32 v81, v33, v41
	v_add_u32_e32 v82, v33, v42
	v_add_u32_e32 v83, s3, v38
	s_lshl_b64 s[66:67], s[54:55], 12
	s_mov_b32 s35, 0xc0c00000
	s_mov_b64 s[68:69], 0x200
	s_mov_b64 s[70:71], 0x400
	s_mov_b64 s[76:77], 0x600
	s_mov_b32 s3, 0xc0f00000
	s_brev_b32 s72, 8
	v_mov_b64_e32 v[74:75], 0xbfff
	v_mov_b64_e32 v[76:77], 0x4000
	v_mov_b32_e32 v84, 0x40c00000
	v_mov_b32_e32 v85, 0x40f00000
	v_mov_b64_e32 v[78:79], v[68:69]
	s_waitcnt vmcnt(7)
	v_mov_b64_e32 v[36:37], v[26:27]
	s_waitcnt vmcnt(6)
	v_mov_b64_e32 v[44:45], v[18:19]
	s_waitcnt vmcnt(5)
	v_mov_b64_e32 v[52:53], v[10:11]
	s_waitcnt vmcnt(4)
	v_mov_b64_e32 v[60:61], v[2:3]
	s_waitcnt vmcnt(3)
	v_mov_b64_e32 v[40:41], v[30:31]
	s_waitcnt vmcnt(2)
	v_mov_b64_e32 v[48:49], v[22:23]
	s_waitcnt vmcnt(1)
	v_mov_b64_e32 v[56:57], v[14:15]
	s_waitcnt vmcnt(0)
	v_mov_b64_e32 v[64:65], v[6:7]
	v_mov_b64_e32 v[34:35], v[24:25]
	v_mov_b64_e32 v[42:43], v[16:17]
	v_mov_b64_e32 v[50:51], v[8:9]
	v_mov_b64_e32 v[58:59], v[0:1]
	v_mov_b64_e32 v[38:39], v[28:29]
	v_mov_b64_e32 v[46:47], v[20:21]
	v_mov_b64_e32 v[54:55], v[12:13]
	v_mov_b64_e32 v[62:63], v[4:5]
	s_branch .LBB0_52
